# row-wise LayerNorm phases (post-mixer, post-FFN): next row's 4 loads prefetched at row start into spare VGPRs, vmcnt(5) at loop end; plus attention mask paths without per-element SALU and s_nop
# speedup vs baseline: 1.0132x; 1.0107x over previous
.Lw3_h0_mask:
	v_sub_u32_e32 v139, s99, v125
	v_cmp_le_i32_e32 vcc, 0, v139
	v_cndmask_b32_e32 v34, v184, v34, vcc
	v_cmp_le_i32_e32 vcc, 1, v139
	v_cndmask_b32_e32 v35, v184, v35, vcc
	v_cmp_le_i32_e32 vcc, 2, v139
	v_cndmask_b32_e32 v36, v184, v36, vcc
	v_cmp_le_i32_e32 vcc, 3, v139
	v_cndmask_b32_e32 v37, v184, v37, vcc
	v_cmp_le_i32_e32 vcc, -16, v139
	v_cndmask_b32_e32 v38, v184, v38, vcc
	v_cmp_le_i32_e32 vcc, -15, v139
	v_cndmask_b32_e32 v39, v184, v39, vcc
	v_cmp_le_i32_e32 vcc, -14, v139
	v_cndmask_b32_e32 v40, v184, v40, vcc
	v_cmp_le_i32_e32 vcc, -13, v139
	v_cndmask_b32_e32 v41, v184, v41, vcc
	v_cmp_le_i32_e32 vcc, 8, v139
	v_cndmask_b32_e32 v42, v184, v42, vcc
	v_cmp_le_i32_e32 vcc, 9, v139
	v_cndmask_b32_e32 v43, v184, v43, vcc
	v_cmp_le_i32_e32 vcc, 10, v139
	v_cndmask_b32_e32 v44, v184, v44, vcc
	v_cmp_le_i32_e32 vcc, 11, v139
	v_cndmask_b32_e32 v45, v184, v45, vcc
	v_cmp_le_i32_e32 vcc, -8, v139
	v_cndmask_b32_e32 v46, v184, v46, vcc
	v_cmp_le_i32_e32 vcc, -7, v139
	v_cndmask_b32_e32 v47, v184, v47, vcc
	v_cmp_le_i32_e32 vcc, -6, v139
	v_cndmask_b32_e32 v48, v184, v48, vcc
	v_cmp_le_i32_e32 vcc, -5, v139
	v_cndmask_b32_e32 v49, v184, v49, vcc
	s_branch .Lw3_h0_sm
.Lw3_h0_wmask:
	v_sub_u32_e32 v139, s99, v125
	v_add_u32_e32 v139, 0xffffff81, v139
	v_cmp_ge_i32_e32 vcc, 0, v139
	v_cndmask_b32_e32 v34, v184, v34, vcc
	v_cmp_ge_i32_e32 vcc, 1, v139
	v_cndmask_b32_e32 v35, v184, v35, vcc
	v_cmp_ge_i32_e32 vcc, 2, v139
	v_cndmask_b32_e32 v36, v184, v36, vcc
	v_cmp_ge_i32_e32 vcc, 3, v139
	v_cndmask_b32_e32 v37, v184, v37, vcc
	v_cmp_ge_i32_e32 vcc, -16, v139
	v_cndmask_b32_e32 v38, v184, v38, vcc
	v_cmp_ge_i32_e32 vcc, -15, v139
	v_cndmask_b32_e32 v39, v184, v39, vcc
	v_cmp_ge_i32_e32 vcc, -14, v139
	v_cndmask_b32_e32 v40, v184, v40, vcc
	v_cmp_ge_i32_e32 vcc, -13, v139
	v_cndmask_b32_e32 v41, v184, v41, vcc
	v_cmp_ge_i32_e32 vcc, 8, v139
	v_cndmask_b32_e32 v42, v184, v42, vcc
	v_cmp_ge_i32_e32 vcc, 9, v139
	v_cndmask_b32_e32 v43, v184, v43, vcc
	v_cmp_ge_i32_e32 vcc, 10, v139
	v_cndmask_b32_e32 v44, v184, v44, vcc
	v_cmp_ge_i32_e32 vcc, 11, v139
	v_cndmask_b32_e32 v45, v184, v45, vcc
	v_cmp_ge_i32_e32 vcc, -8, v139
	v_cndmask_b32_e32 v46, v184, v46, vcc
	v_cmp_ge_i32_e32 vcc, -7, v139
	v_cndmask_b32_e32 v47, v184, v47, vcc
	v_cmp_ge_i32_e32 vcc, -6, v139
	v_cndmask_b32_e32 v48, v184, v48, vcc
	v_cmp_ge_i32_e32 vcc, -5, v139
	v_cndmask_b32_e32 v49, v184, v49, vcc
	s_branch .Lw3_h0_sm

.Lv3_h0_mask:
	s_sub_i32 s13, s12, s91
	v_sub_u32_e32 v244, s13, v197
	v_cmp_le_i32_e32 vcc, 0, v244
	v_cndmask_b32_e32 v66, v184, v66, vcc
	v_cmp_le_i32_e32 vcc, 1, v244
	v_cndmask_b32_e32 v67, v184, v67, vcc
	v_cmp_le_i32_e32 vcc, 2, v244
	v_cndmask_b32_e32 v68, v184, v68, vcc
	v_cmp_le_i32_e32 vcc, 3, v244
	v_cndmask_b32_e32 v69, v184, v69, vcc
	v_cmp_le_i32_e32 vcc, -16, v244
	v_cndmask_b32_e32 v70, v184, v70, vcc
	v_cmp_le_i32_e32 vcc, -15, v244
	v_cndmask_b32_e32 v71, v184, v71, vcc
	v_cmp_le_i32_e32 vcc, -14, v244
	v_cndmask_b32_e32 v72, v184, v72, vcc
	v_cmp_le_i32_e32 vcc, -13, v244
	v_cndmask_b32_e32 v73, v184, v73, vcc
	v_cmp_le_i32_e32 vcc, 8, v244
	v_cndmask_b32_e32 v74, v184, v74, vcc
	v_cmp_le_i32_e32 vcc, 9, v244
	v_cndmask_b32_e32 v75, v184, v75, vcc
	v_cmp_le_i32_e32 vcc, 10, v244
	v_cndmask_b32_e32 v76, v184, v76, vcc
	v_cmp_le_i32_e32 vcc, 11, v244
	v_cndmask_b32_e32 v77, v184, v77, vcc
	v_cmp_le_i32_e32 vcc, -8, v244
	v_cndmask_b32_e32 v78, v184, v78, vcc
	v_cmp_le_i32_e32 vcc, -7, v244
	v_cndmask_b32_e32 v79, v184, v79, vcc
	v_cmp_le_i32_e32 vcc, -6, v244
	v_cndmask_b32_e32 v80, v184, v80, vcc
	v_cmp_le_i32_e32 vcc, -5, v244
	v_cndmask_b32_e32 v81, v184, v81, vcc
	s_branch .Lv3_h0_sm

.LBB0_892:
	s_lshl_b64 s[6:7], s[10:11], 2
	s_mov_b64 s[4:5], 0
	s_add_u32 s10, s62, s6
	v_mov_b32_e32 v0, v162
	s_addc_u32 s11, s63, s7
	v_readlane_b32 s12, v246, 39
	v_ashrrev_i32_e32 v2, 6, v0
	s_add_u32 s80, s64, s6
	v_add_u32_e32 v50, s12, v2
	s_movk_i32 s12, 0x4000
	s_addc_u32 s81, s65, s7
	v_cmp_gt_i32_e32 vcc, s12, v50
	s_and_saveexec_b64 s[58:59], vcc
	s_cbranch_execz .LBB0_897
	s_add_u32 s4, s50, s4
	s_addc_u32 s5, s51, s5
	s_add_u32 s82, s4, 0x80000
	s_addc_u32 s83, s5, 0
	s_lshl_b64 s[60:61], s[8:9], 2
	s_add_u32 s60, s4, s60
	v_and_b32_e32 v51, 63, v0
	s_addc_u32 s61, s5, s61
	v_lshlrev_b32_e32 v0, 4, v51
	v_lshl_add_u64 v[2:3], s[60:61], 0, v[0:1]
	s_movk_i32 s40, 0x5000
	s_mov_b64 s[60:61], 0x5000
	v_add_co_u32_e32 v4, vcc, s40, v2
	v_lshl_add_u64 v[34:35], v[2:3], 0, s[60:61]
	s_mov_b64 s[60:61], 0x4000
	v_addc_co_u32_e32 v5, vcc, 0, v3, vcc
	v_lshl_add_u64 v[46:47], v[2:3], 0, s[60:61]
	v_add_co_u32_e32 v2, vcc, s12, v2
	v_mov_b32_e32 v53, v1
	s_nop 0
	v_addc_co_u32_e32 v3, vcc, 0, v3, vcc
	global_load_dwordx4 v[56:59], v[4:5], off
	s_nop 0
	global_load_dwordx4 v[2:5], v[2:3], off
	s_nop 0
	global_load_dwordx4 v[6:9], v0, s[10:11]
	global_load_dwordx4 v[10:13], v0, s[10:11] offset:1024
	global_load_dwordx4 v[14:17], v0, s[80:81]
	global_load_dwordx4 v[18:21], v0, s[80:81] offset:1024
	s_waitcnt lgkmcnt(0)
	global_load_dwordx4 v[60:63], v[34:35], off offset:1024
	global_load_dwordx4 v[64:67], v[34:35], off offset:2048
	global_load_dwordx4 v[22:25], v0, s[10:11] offset:2048
	global_load_dwordx4 v[26:29], v0, s[10:11] offset:3072
	global_load_dwordx4 v[30:33], v[46:47], off offset:1024
	global_load_dwordx4 v[68:71], v[34:35], off offset:3072
	s_nop 0
	global_load_dwordx4 v[34:37], v0, s[80:81] offset:2048
	global_load_dwordx4 v[38:41], v0, s[80:81] offset:3072
	global_load_dwordx4 v[42:45], v[46:47], off offset:2048
	s_nop 0
	global_load_dwordx4 v[46:49], v[46:47], off offset:3072
	v_lshlrev_b32_e32 v52, 3, v51
	v_lshl_add_u64 v[54:55], s[4:5], 0, v[0:1]
	s_waitcnt vmcnt(24)
	v_lshl_add_u64 v[72:73], s[4:5], 0, v[52:53]
	s_mov_b64 s[4:5], 0x100000
	v_lshlrev_b32_e32 v74, 2, v51
	v_lshl_add_u64 v[52:53], v[54:55], 0, s[4:5]
	s_mov_b64 s[4:5], 0x4100000
	v_cmp_eq_u32_e32 vcc, 0, v51
	v_xor_b32_e32 v90, 0x80, v74
	v_xor_b32_e32 v91, 64, v74
	v_xor_b32_e32 v92, 32, v74
	v_xor_b32_e32 v93, 16, v74
	v_xor_b32_e32 v94, 8, v74
	v_xor_b32_e32 v95, 4, v74
	v_lshl_add_u64 v[54:55], v[72:73], 0, s[4:5]
	s_mov_b64 s[84:85], 0
	s_waitcnt vmcnt(15)
	v_pk_add_f32 v[56:57], v[56:57], 1.0 op_sel_hi:[1,0]
	v_pk_add_f32 v[58:59], v[58:59], 1.0 op_sel_hi:[1,0]
	s_waitcnt vmcnt(9)
	v_pk_add_f32 v[60:61], v[60:61], 1.0 op_sel_hi:[1,0]
	v_pk_add_f32 v[62:63], v[62:63], 1.0 op_sel_hi:[1,0]
	s_waitcnt vmcnt(8)
	v_pk_add_f32 v[64:65], v[64:65], 1.0 op_sel_hi:[1,0]
	v_pk_add_f32 v[66:67], v[66:67], 1.0 op_sel_hi:[1,0]
	s_waitcnt vmcnt(4)
	v_pk_add_f32 v[68:69], v[68:69], 1.0 op_sel_hi:[1,0]
	v_pk_add_f32 v[70:71], v[70:71], 1.0 op_sel_hi:[1,0]
	v_ashrrev_i32_e32 v119, 31, v50
	v_mov_b32_e32 v118, v50
	v_lshlrev_b64 v[120:121], 12, v[118:119]
	v_lshl_add_u64 v[120:121], v[52:53], 0, v[120:121]
	global_load_dwordx4 v[102:105], v[120:121], off
	global_load_dwordx4 v[106:109], v[120:121], off offset:1024
	global_load_dwordx4 v[110:113], v[120:121], off offset:2048
	global_load_dwordx4 v[114:117], v[120:121], off offset:3072
	s_waitcnt vmcnt(0)
	s_branch .LBB0_895
.LBB0_894:
	s_or_b64 exec, exec, s[4:5]
	v_pk_mul_f32 v[72:73], v[72:73], v[0:1] op_sel_hi:[1,0]
	v_pk_mul_f32 v[74:75], v[74:75], v[0:1] op_sel_hi:[1,0]
	v_pk_fma_f32 v[72:73], v[6:7], v[72:73], v[14:15]
	v_pk_fma_f32 v[74:75], v[8:9], v[74:75], v[16:17]
	v_pk_mul_f32 v[80:81], v[82:83], v[0:1] op_sel_hi:[1,0]
	v_pk_mul_f32 v[82:83], v[84:85], v[0:1] op_sel_hi:[1,0]
	v_pk_mul_f32 v[84:85], v[86:87], v[0:1] op_sel_hi:[1,0]
	v_pk_mul_f32 v[86:87], v[88:89], v[0:1] op_sel_hi:[1,0]
	v_lshlrev_b64 v[88:89], 11, v[50:51]
	v_pk_fma_f32 v[72:73], v[72:73], v[56:57], v[2:3]
	v_pk_fma_f32 v[74:75], v[74:75], v[58:59], v[4:5]
	v_pk_mul_f32 v[76:77], v[76:77], v[0:1] op_sel_hi:[1,0]
	v_pk_mul_f32 v[78:79], v[78:79], v[0:1] op_sel_hi:[1,0]
	v_lshl_add_u64 v[88:89], v[54:55], 0, v[88:89]
	v_cvt_pk_bf16_f32 v72, v72, v73
	v_cvt_pk_bf16_f32 v73, v74, v75
	global_store_dwordx2 v[88:89], v[72:73], off
	v_pk_fma_f32 v[72:73], v[10:11], v[76:77], v[18:19]
	v_pk_fma_f32 v[74:75], v[12:13], v[78:79], v[20:21]
	v_pk_fma_f32 v[72:73], v[72:73], v[60:61], v[30:31]
	v_pk_fma_f32 v[74:75], v[74:75], v[62:63], v[32:33]
	v_cvt_pk_bf16_f32 v72, v72, v73
	v_cvt_pk_bf16_f32 v73, v74, v75
	global_store_dwordx2 v[88:89], v[72:73], off offset:512
	v_pk_fma_f32 v[72:73], v[22:23], v[80:81], v[34:35]
	v_pk_fma_f32 v[74:75], v[24:25], v[82:83], v[36:37]
	v_pk_fma_f32 v[72:73], v[72:73], v[64:65], v[42:43]
	v_pk_fma_f32 v[74:75], v[74:75], v[66:67], v[44:45]
	v_cvt_pk_bf16_f32 v72, v72, v73
	v_cvt_pk_bf16_f32 v73, v74, v75
	global_store_dwordx2 v[88:89], v[72:73], off offset:1024
	v_pk_fma_f32 v[72:73], v[26:27], v[84:85], v[38:39]
	v_pk_fma_f32 v[74:75], v[28:29], v[86:87], v[40:41]
	v_add_u32_e32 v50, s71, v50
	v_pk_fma_f32 v[72:73], v[72:73], v[68:69], v[46:47]
	v_pk_fma_f32 v[74:75], v[74:75], v[70:71], v[48:49]
	v_cmp_lt_i32_e64 s[4:5], s43, v50
	v_cvt_pk_bf16_f32 v72, v72, v73
	v_cvt_pk_bf16_f32 v73, v74, v75
	s_or_b64 s[84:85], s[4:5], s[84:85]
	global_store_dwordx2 v[88:89], v[72:73], off offset:1536
	s_andn2_b64 exec, exec, s[84:85]
	s_cbranch_execz .LBB0_897
	s_waitcnt vmcnt(5)
.LBB0_895:
	v_ashrrev_i32_e32 v51, 31, v50
	v_mov_b64_e32 v[72:73], v[102:103]
	v_mov_b64_e32 v[74:75], v[104:105]
	v_mov_b64_e32 v[76:77], v[106:107]
	v_mov_b64_e32 v[78:79], v[108:109]
	v_mov_b64_e32 v[82:83], v[110:111]
	v_mov_b64_e32 v[84:85], v[112:113]
	v_mov_b64_e32 v[86:87], v[114:115]
	v_mov_b64_e32 v[88:89], v[116:117]
	v_add_u32_e32 v118, s71, v50
	v_min_i32_e32 v118, s43, v118
	v_mov_b32_e32 v119, 0
	v_lshlrev_b64 v[120:121], 12, v[118:119]
	v_lshl_add_u64 v[120:121], v[52:53], 0, v[120:121]
	global_load_dwordx4 v[102:105], v[120:121], off
	global_load_dwordx4 v[106:109], v[120:121], off offset:1024
	global_load_dwordx4 v[110:113], v[120:121], off offset:2048
	global_load_dwordx4 v[114:117], v[120:121], off offset:3072
	v_mov_b32_e32 v96, v72
	v_mov_b32_e32 v97, v76
	v_mov_b32_e32 v98, v73
	v_mov_b32_e32 v99, v77
	v_pk_add_f32 v[96:97], v[96:97], v[98:99]
	v_mov_b32_e32 v98, v74
	v_mov_b32_e32 v99, v78
	v_pk_add_f32 v[96:97], v[96:97], v[98:99]
	v_mov_b32_e32 v98, v75
	v_mov_b32_e32 v99, v79
	v_pk_add_f32 v[96:97], v[96:97], v[98:99]
	s_nop 0
	v_add_f32_e32 v0, 0, v96
	v_add_f32_e32 v0, v0, v97
	v_mov_b32_e32 v80, v82
	v_mov_b32_e32 v81, v86
	v_mov_b32_e32 v96, v83
	v_mov_b32_e32 v97, v87
	v_pk_add_f32 v[80:81], v[80:81], v[96:97]
	v_mov_b32_e32 v96, v84
	v_mov_b32_e32 v97, v88
	v_pk_add_f32 v[80:81], v[80:81], v[96:97]
	v_mov_b32_e32 v96, v85
	v_mov_b32_e32 v97, v89
	v_pk_add_f32 v[80:81], v[80:81], v[96:97]
	s_nop 0
	v_add_f32_e32 v0, v0, v80
	v_add_f32_e32 v0, v0, v81
	ds_bpermute_b32 v80, v90, v0
	s_waitcnt lgkmcnt(0)
	v_add_f32_e32 v0, v0, v80
	ds_bpermute_b32 v80, v91, v0
	s_waitcnt lgkmcnt(0)
	v_add_f32_e32 v0, v0, v80
	ds_bpermute_b32 v80, v92, v0
	s_waitcnt lgkmcnt(0)
	v_add_f32_e32 v0, v0, v80
	ds_bpermute_b32 v80, v93, v0
	s_waitcnt lgkmcnt(0)
	v_add_f32_e32 v0, v0, v80
	ds_bpermute_b32 v80, v94, v0
	s_waitcnt lgkmcnt(0)
	v_add_f32_e32 v0, v0, v80
	ds_bpermute_b32 v80, v95, v0
	s_waitcnt lgkmcnt(0)
	v_add_f32_e32 v0, v0, v80
	v_mul_f32_e32 v80, 0x3a800000, v0
	v_pk_add_f32 v[72:73], v[72:73], v[80:81] op_sel_hi:[1,0] neg_lo:[0,1] neg_hi:[0,1]
	v_pk_add_f32 v[76:77], v[76:77], v[80:81] op_sel_hi:[1,0] neg_lo:[0,1] neg_hi:[0,1]
	v_mov_b32_e32 v98, v73
	v_mov_b32_e32 v99, v77
	v_pk_add_f32 v[74:75], v[74:75], v[80:81] op_sel_hi:[1,0] neg_lo:[0,1] neg_hi:[0,1]
	v_pk_add_f32 v[78:79], v[78:79], v[80:81] op_sel_hi:[1,0] neg_lo:[0,1] neg_hi:[0,1]
	v_mov_b32_e32 v96, v72
	v_mov_b32_e32 v97, v76
	v_pk_mul_f32 v[98:99], v[98:99], v[98:99]
	v_pk_add_f32 v[82:83], v[82:83], v[80:81] op_sel_hi:[1,0] neg_lo:[0,1] neg_hi:[0,1]
	v_pk_fma_f32 v[96:97], v[96:97], v[96:97], v[98:99]
	v_mov_b32_e32 v98, v74
	v_mov_b32_e32 v99, v78
	v_pk_add_f32 v[86:87], v[86:87], v[80:81] op_sel_hi:[1,0] neg_lo:[0,1] neg_hi:[0,1]
	v_pk_fma_f32 v[96:97], v[98:99], v[98:99], v[96:97]
	v_mov_b32_e32 v98, v75
	v_mov_b32_e32 v99, v79
	v_mov_b32_e32 v100, v87
	v_mov_b32_e32 v101, v83
	v_pk_fma_f32 v[96:97], v[98:99], v[98:99], v[96:97]
	v_pk_add_f32 v[84:85], v[84:85], v[80:81] op_sel_hi:[1,0] neg_lo:[0,1] neg_hi:[0,1]
	v_pk_add_f32 v[88:89], v[88:89], v[80:81] op_sel_hi:[1,0] neg_lo:[0,1] neg_hi:[0,1]
	v_mov_b32_e32 v98, v86
	v_mov_b32_e32 v99, v82
	v_pk_mul_f32 v[100:101], v[100:101], v[100:101]
	v_add_f32_e32 v0, v96, v97
	v_pk_fma_f32 v[98:99], v[98:99], v[98:99], v[100:101]
	v_mov_b32_e32 v100, v88
	v_mov_b32_e32 v101, v84
	v_pk_fma_f32 v[98:99], v[100:101], v[100:101], v[98:99]
	v_mov_b32_e32 v100, v89
	v_mov_b32_e32 v101, v85
	v_pk_fma_f32 v[98:99], v[100:101], v[100:101], v[98:99]
	s_nop 0
	v_add_f32_e32 v0, v99, v0
	v_add_f32_e32 v0, v98, v0
	ds_bpermute_b32 v81, v90, v0
	s_waitcnt lgkmcnt(0)
	v_add_f32_e32 v0, v0, v81
	ds_bpermute_b32 v81, v91, v0
	s_waitcnt lgkmcnt(0)
	v_add_f32_e32 v0, v0, v81
	ds_bpermute_b32 v81, v92, v0
	s_waitcnt lgkmcnt(0)
	v_add_f32_e32 v0, v0, v81
	ds_bpermute_b32 v81, v93, v0
	s_waitcnt lgkmcnt(0)
	v_add_f32_e32 v0, v0, v81
	ds_bpermute_b32 v81, v94, v0
	s_waitcnt lgkmcnt(0)
	v_add_f32_e32 v0, v0, v81
	ds_bpermute_b32 v81, v95, v0
	s_waitcnt lgkmcnt(0)
	v_add_f32_e32 v0, v0, v81
	v_fmamk_f32 v0, v0, 0x3a800000, v178
	v_cmp_gt_f32_e64 s[4:5], s42, v0
	v_mul_f32_e32 v81, 0x4b800000, v0
	s_nop 0
	v_cndmask_b32_e64 v0, v0, v81, s[4:5]
	v_rsq_f32_e32 v0, v0
	s_nop 0
	v_mul_f32_e32 v81, 0x45800000, v0
	v_cndmask_b32_e64 v0, v0, v81, s[4:5]
	s_and_saveexec_b64 s[4:5], vcc
	s_cbranch_execz .LBB0_894
	v_lshl_add_u64 v[96:97], v[50:51], 3, s[82:83]
	v_mov_b32_e32 v81, v0
	global_store_dwordx2 v[96:97], v[80:81], off
	s_branch .LBB0_894

.LBB0_1091:
	v_mov_b32_e32 v0, v162
	v_readlane_b32 s4, v246, 39
	v_ashrrev_i32_e32 v2, 6, v0
	s_nop 0
	v_add_u32_e32 v50, s4, v2
	s_movk_i32 s4, 0x4000
	v_cmp_gt_i32_e32 vcc, s4, v50
	s_and_saveexec_b64 s[80:81], vcc
	s_cbranch_execz .LBB0_1096
	s_add_u32 s82, s58, 0x80000
	s_addc_u32 s83, s59, 0
	s_lshl_b64 s[4:5], s[8:9], 2
	s_add_u32 s60, s58, s4
	v_and_b32_e32 v51, 63, v0
	s_addc_u32 s61, s59, s5
	v_readlane_b32 s12, v246, 21
	v_lshlrev_b32_e32 v0, 4, v51
	v_readlane_b32 s13, v246, 22
	v_lshl_add_u64 v[2:3], s[60:61], 0, v[0:1]
	s_mov_b32 s40, 0x8000
	s_mov_b64 s[4:5], s[12:13]
	s_mov_b64 s[60:61], 0x8000
	v_add_co_u32_e32 v4, vcc, s40, v2
	s_add_u32 s8, s4, s6
	v_lshl_add_u64 v[34:35], v[2:3], 0, s[60:61]
	s_mov_b64 s[60:61], 0x7000
	v_addc_co_u32_e32 v5, vcc, 0, v3, vcc
	s_movk_i32 s40, 0x7000
	s_addc_u32 s9, s5, s7
	v_lshl_add_u64 v[38:39], v[2:3], 0, s[60:61]
	v_add_co_u32_e32 v2, vcc, s40, v2
	s_add_u32 s4, s66, s6
	s_nop 0
	v_addc_co_u32_e32 v3, vcc, 0, v3, vcc
	s_addc_u32 s5, s67, s7
	global_load_dwordx4 v[56:59], v[4:5], off
	s_nop 0
	global_load_dwordx4 v[2:5], v[2:3], off
	s_nop 0
	global_load_dwordx4 v[6:9], v0, s[4:5]
	global_load_dwordx4 v[10:13], v0, s[4:5] offset:1024
	global_load_dwordx4 v[14:17], v0, s[8:9]
	global_load_dwordx4 v[18:21], v0, s[8:9] offset:1024
	global_load_dwordx4 v[60:63], v[34:35], off offset:1024
	global_load_dwordx4 v[64:67], v[34:35], off offset:2048
	global_load_dwordx4 v[22:25], v0, s[8:9] offset:2048
	global_load_dwordx4 v[26:29], v0, s[8:9] offset:3072
	global_load_dwordx4 v[30:33], v[38:39], off offset:1024
	global_load_dwordx4 v[68:71], v[34:35], off offset:3072
	s_nop 0
	global_load_dwordx4 v[34:37], v[38:39], off offset:2048
	s_nop 0
	global_load_dwordx4 v[38:41], v[38:39], off offset:3072
	s_nop 0
	global_load_dwordx4 v[42:45], v0, s[4:5] offset:2048
	global_load_dwordx4 v[46:49], v0, s[4:5] offset:3072
	v_mov_b32_e32 v53, v1
	v_lshlrev_b32_e32 v52, 3, v51
	v_lshl_add_u64 v[54:55], s[58:59], 0, v[0:1]
	s_mov_b64 s[4:5], 0x100000
	v_lshlrev_b32_e32 v74, 2, v51
	s_waitcnt vmcnt(24)
	v_lshl_add_u64 v[72:73], s[58:59], 0, v[52:53]
	v_lshl_add_u64 v[52:53], v[54:55], 0, s[4:5]
	s_mov_b64 s[4:5], 0x4100000
	v_cmp_eq_u32_e32 vcc, 0, v51
	v_xor_b32_e32 v90, 0x80, v74
	v_xor_b32_e32 v91, 64, v74
	v_xor_b32_e32 v92, 32, v74
	v_xor_b32_e32 v93, 16, v74
	v_xor_b32_e32 v94, 8, v74
	v_xor_b32_e32 v95, 4, v74
	v_lshl_add_u64 v[54:55], v[72:73], 0, s[4:5]
	s_mov_b64 s[8:9], 0
	v_readlane_b32 s14, v246, 23
	v_readlane_b32 s15, v246, 24
	v_readlane_b32 s16, v246, 25
	v_readlane_b32 s17, v246, 26
	v_readlane_b32 s18, v246, 27
	v_readlane_b32 s19, v246, 28
	v_readlane_b32 s20, v246, 29
	v_readlane_b32 s21, v246, 30
	v_readlane_b32 s22, v246, 31
	v_readlane_b32 s23, v246, 32
	v_readlane_b32 s24, v246, 33
	v_readlane_b32 s25, v246, 34
	v_readlane_b32 s26, v246, 35
	v_readlane_b32 s27, v246, 36
	s_waitcnt vmcnt(15)
	v_pk_add_f32 v[56:57], v[56:57], 1.0 op_sel_hi:[1,0]
	v_pk_add_f32 v[58:59], v[58:59], 1.0 op_sel_hi:[1,0]
	s_waitcnt vmcnt(9)
	v_pk_add_f32 v[60:61], v[60:61], 1.0 op_sel_hi:[1,0]
	v_pk_add_f32 v[62:63], v[62:63], 1.0 op_sel_hi:[1,0]
	s_waitcnt vmcnt(8)
	v_pk_add_f32 v[64:65], v[64:65], 1.0 op_sel_hi:[1,0]
	v_pk_add_f32 v[66:67], v[66:67], 1.0 op_sel_hi:[1,0]
	s_waitcnt vmcnt(4)
	v_pk_add_f32 v[68:69], v[68:69], 1.0 op_sel_hi:[1,0]
	v_pk_add_f32 v[70:71], v[70:71], 1.0 op_sel_hi:[1,0]
	v_ashrrev_i32_e32 v119, 31, v50
	v_mov_b32_e32 v118, v50
	v_lshlrev_b64 v[120:121], 12, v[118:119]
	v_lshl_add_u64 v[120:121], v[52:53], 0, v[120:121]
	global_load_dwordx4 v[102:105], v[120:121], off
	global_load_dwordx4 v[106:109], v[120:121], off offset:1024
	global_load_dwordx4 v[110:113], v[120:121], off offset:2048
	global_load_dwordx4 v[114:117], v[120:121], off offset:3072
	s_waitcnt vmcnt(0)
	s_branch .LBB0_1094
.LBB0_1093:
	s_or_b64 exec, exec, s[4:5]
	v_pk_mul_f32 v[72:73], v[72:73], v[0:1] op_sel_hi:[1,0]
	v_pk_mul_f32 v[74:75], v[74:75], v[0:1] op_sel_hi:[1,0]
	v_pk_fma_f32 v[72:73], v[6:7], v[72:73], v[14:15]
	v_pk_fma_f32 v[74:75], v[8:9], v[74:75], v[16:17]
	v_pk_mul_f32 v[80:81], v[82:83], v[0:1] op_sel_hi:[1,0]
	v_pk_mul_f32 v[82:83], v[84:85], v[0:1] op_sel_hi:[1,0]
	v_pk_mul_f32 v[84:85], v[86:87], v[0:1] op_sel_hi:[1,0]
	v_pk_mul_f32 v[86:87], v[88:89], v[0:1] op_sel_hi:[1,0]
	v_lshlrev_b64 v[88:89], 11, v[50:51]
	v_pk_fma_f32 v[72:73], v[72:73], v[56:57], v[2:3]
	v_pk_fma_f32 v[74:75], v[74:75], v[58:59], v[4:5]
	v_pk_mul_f32 v[76:77], v[76:77], v[0:1] op_sel_hi:[1,0]
	v_pk_mul_f32 v[78:79], v[78:79], v[0:1] op_sel_hi:[1,0]
	v_lshl_add_u64 v[88:89], v[54:55], 0, v[88:89]
	v_cvt_pk_bf16_f32 v72, v72, v73
	v_cvt_pk_bf16_f32 v73, v74, v75
	global_store_dwordx2 v[88:89], v[72:73], off
	v_pk_fma_f32 v[72:73], v[10:11], v[76:77], v[18:19]
	v_pk_fma_f32 v[74:75], v[12:13], v[78:79], v[20:21]
	v_pk_fma_f32 v[72:73], v[72:73], v[60:61], v[30:31]
	v_pk_fma_f32 v[74:75], v[74:75], v[62:63], v[32:33]
	v_cvt_pk_bf16_f32 v72, v72, v73
	v_cvt_pk_bf16_f32 v73, v74, v75
	global_store_dwordx2 v[88:89], v[72:73], off offset:512
	v_pk_fma_f32 v[72:73], v[42:43], v[80:81], v[22:23]
	v_pk_fma_f32 v[74:75], v[44:45], v[82:83], v[24:25]
	v_pk_fma_f32 v[72:73], v[72:73], v[64:65], v[34:35]
	v_pk_fma_f32 v[74:75], v[74:75], v[66:67], v[36:37]
	v_cvt_pk_bf16_f32 v72, v72, v73
	v_cvt_pk_bf16_f32 v73, v74, v75
	global_store_dwordx2 v[88:89], v[72:73], off offset:1024
	v_pk_fma_f32 v[72:73], v[46:47], v[84:85], v[26:27]
	v_pk_fma_f32 v[74:75], v[48:49], v[86:87], v[28:29]
	v_add_u32_e32 v50, s71, v50
	v_pk_fma_f32 v[72:73], v[72:73], v[68:69], v[38:39]
	v_pk_fma_f32 v[74:75], v[74:75], v[70:71], v[40:41]
	v_cmp_lt_i32_e64 s[4:5], s43, v50
	v_cvt_pk_bf16_f32 v72, v72, v73
	v_cvt_pk_bf16_f32 v73, v74, v75
	s_or_b64 s[8:9], s[4:5], s[8:9]
	global_store_dwordx2 v[88:89], v[72:73], off offset:1536
	s_andn2_b64 exec, exec, s[8:9]
	s_cbranch_execz .LBB0_1096
	s_waitcnt vmcnt(5)

.LBB0_1096:
	s_waitcnt vmcnt(0)
	s_or_b64 exec, exec, s[80:81]
	s_cbranch_execnz .LBB0_1090
